# group-local barriers use one monotonic arrival counter (no separate release word)
# baseline (speedup 1.0000x reference)
; __device__ __forceinline__ unsigned xb_ld(unsigned* p)              { return __hip_atomic_load(p, __ATOMIC_RELAXED, __HIP_MEMORY_SCOPE_AGENT); }
; __device__ __forceinline__ unsigned xb_add(unsigned* p, unsigned v) { return __hip_atomic_fetch_add(p, v, __ATOMIC_RELAXED, __HIP_MEMORY_SCOPE_AGENT); }
; #define XB_SPIN(cond, bar) do { unsigned _sp = 0; while (cond) { __builtin_amdgcn_s_sleep(1); \
;     if ((++_sp & 255u) == 0u) { if (xb_ld(&(bar)[XB_TMO])) break; if (_sp > XB_SPIN_CAP) { atomicAdd(&(bar)[XB_TMO], 1u); break; } } } } while (0)
; __device__ __forceinline__ void xcd_barrier(const XcdBarrier& b) {
;     asm volatile("s_waitcnt vmcnt(0)" ::: "memory");
;     __syncthreads();
;     if (threadIdx.x == 0) {
;         unsigned* bar = b.bar;
;         __builtin_amdgcn_s_waitcnt(0);
;         unsigned nloc = b.st[0], nx = b.st[1];
;         if (nloc == 0u) { xcd_barrier_complete(bar, b.x, nloc, nx); b.st[0] = nloc; b.st[1] = nx; }
;         const unsigned old = xb_add(&bar[XB_XSUB(b.x)], 1u);
;         const unsigned gen = old / nloc;
;         if (old + 1u == (gen + 1u) * nloc) {
;             __builtin_amdgcn_fence(__ATOMIC_RELEASE, "agent");
;             asm volatile("s_waitcnt vmcnt(0)" ::: "memory");
;             const unsigned og = xb_add(&bar[XB_TOP], 1u);
;             const unsigned tg = og / nx;
;             if (og + 1u == (tg + 1u) * nx) xb_add(&bar[XB_TOPGEN], 1u);
;             else XB_SPIN(xb_ld(&bar[XB_TOPGEN]) == tg, bar);
;             __builtin_amdgcn_fence(__ATOMIC_ACQUIRE, "agent");
;             xb_add(&bar[XB_XGEN(b.x)], 1u);
;             asm volatile("s_waitcnt vmcnt(0)" ::: "memory");
;         } else {
;             XB_SPIN(xb_ld(&bar[XB_XGEN(b.x)]) == gen, bar);
;             __builtin_amdgcn_fence(__ATOMIC_ACQUIRE, "agent");
;             asm volatile("s_waitcnt vmcnt(0)" ::: "memory");
;         }
;     }
;     __syncthreads();
.LBB0_251:
	s_cmp_gt_i32 s71, 3
	s_cselect_b64 s[0:1], -1, 0
	s_and_b64 s[6:7], s[6:7], s[0:1]
	s_andn2_b64 vcc, exec, s[6:7]
	s_cbranch_vccnz .LBB0_305
	s_waitcnt vmcnt(0)
	s_waitcnt vmcnt(0)
	s_barrier
	s_and_saveexec_b64 s[6:7], s[96:97]
	s_cbranch_execz .LBB0_304
	s_cmp_eq_u32 s99, 1
	s_cbranch_scc0 .Lgb2_global
	s_and_b32 s100, s2, 7
	s_lshl_b32 s100, s100, 8
	s_add_u32 s100, s100, 0x2d800
	v_mov_b32_e32 v254, s100
	v_mov_b32_e32 v255, 1
	global_atomic_add v254, v255, s[76:77]
	s_mov_b32 s100, 0
.Lgb2_loop:
	global_load_dword v253, v254, s[76:77] sc1
	s_waitcnt vmcnt(0)
	v_readfirstlane_b32 s98, v253
	s_cmp_ge_u32 s98, 32
	s_cbranch_scc1 .Lgb2_acq
	s_sleep 1
	s_add_u32 s100, s100, 1
	s_cmp_lt_u32 s100, 0x40000
	s_cbranch_scc1 .Lgb2_loop
.Lgb2_acq:
	buffer_inv sc1
	s_waitcnt vmcnt(0)
	s_branch .LBB0_304

; __device__ __forceinline__ unsigned xb_ld(unsigned* p)              { return __hip_atomic_load(p, __ATOMIC_RELAXED, __HIP_MEMORY_SCOPE_AGENT); }
; __device__ __forceinline__ unsigned xb_add(unsigned* p, unsigned v) { return __hip_atomic_fetch_add(p, v, __ATOMIC_RELAXED, __HIP_MEMORY_SCOPE_AGENT); }
; #define XB_SPIN(cond, bar) do { unsigned _sp = 0; while (cond) { __builtin_amdgcn_s_sleep(1); \
;     if ((++_sp & 255u) == 0u) { if (xb_ld(&(bar)[XB_TMO])) break; if (_sp > XB_SPIN_CAP) { atomicAdd(&(bar)[XB_TMO], 1u); break; } } } } while (0)
; __device__ __forceinline__ void xcd_barrier(const XcdBarrier& b) {
;     asm volatile("s_waitcnt vmcnt(0)" ::: "memory");
;     __syncthreads();
;     if (threadIdx.x == 0) {
;         unsigned* bar = b.bar;
;         __builtin_amdgcn_s_waitcnt(0);
;         unsigned nloc = b.st[0], nx = b.st[1];
;         if (nloc == 0u) { xcd_barrier_complete(bar, b.x, nloc, nx); b.st[0] = nloc; b.st[1] = nx; }
;         const unsigned old = xb_add(&bar[XB_XSUB(b.x)], 1u);
;         const unsigned gen = old / nloc;
;         if (old + 1u == (gen + 1u) * nloc) {
;             __builtin_amdgcn_fence(__ATOMIC_RELEASE, "agent");
;             asm volatile("s_waitcnt vmcnt(0)" ::: "memory");
;             const unsigned og = xb_add(&bar[XB_TOP], 1u);
;             const unsigned tg = og / nx;
;             if (og + 1u == (tg + 1u) * nx) xb_add(&bar[XB_TOPGEN], 1u);
;             else XB_SPIN(xb_ld(&bar[XB_TOPGEN]) == tg, bar);
;             __builtin_amdgcn_fence(__ATOMIC_ACQUIRE, "agent");
;             xb_add(&bar[XB_XGEN(b.x)], 1u);
;             asm volatile("s_waitcnt vmcnt(0)" ::: "memory");
;         } else {
;             XB_SPIN(xb_ld(&bar[XB_XGEN(b.x)]) == gen, bar);
;             __builtin_amdgcn_fence(__ATOMIC_ACQUIRE, "agent");
;             asm volatile("s_waitcnt vmcnt(0)" ::: "memory");
;         }
;     }
;     __syncthreads();
.LBB0_618:
	s_cmp_gt_i32 s71, 4
	s_cselect_b64 s[0:1], -1, 0
	s_and_b64 s[4:5], s[6:7], s[0:1]
	s_andn2_b64 vcc, exec, s[4:5]
	s_cbranch_vccnz .LBB0_672
	s_waitcnt vmcnt(0)
	s_waitcnt vmcnt(0)
	s_barrier
	s_and_saveexec_b64 s[4:5], s[96:97]
	s_cbranch_execz .LBB0_671
	s_cmp_eq_u32 s99, 1
	s_cbranch_scc0 .Lgb3_global
	s_and_b32 s100, s2, 7
	s_lshl_b32 s100, s100, 8
	s_add_u32 s100, s100, 0x2d800
	v_mov_b32_e32 v254, s100
	v_mov_b32_e32 v255, 1
	global_atomic_add v254, v255, s[76:77]
	s_mov_b32 s100, 0
.Lgb3_loop:
	global_load_dword v253, v254, s[76:77] sc1
	s_waitcnt vmcnt(0)
	v_readfirstlane_b32 s98, v253
	s_cmp_ge_u32 s98, 64
	s_cbranch_scc1 .Lgb3_acq
	s_sleep 1
	s_add_u32 s100, s100, 1
	s_cmp_lt_u32 s100, 0x40000
	s_cbranch_scc1 .Lgb3_loop

; __device__ __forceinline__ unsigned xb_ld(unsigned* p)              { return __hip_atomic_load(p, __ATOMIC_RELAXED, __HIP_MEMORY_SCOPE_AGENT); }
; __device__ __forceinline__ unsigned xb_add(unsigned* p, unsigned v) { return __hip_atomic_fetch_add(p, v, __ATOMIC_RELAXED, __HIP_MEMORY_SCOPE_AGENT); }
; #define XB_SPIN(cond, bar) do { unsigned _sp = 0; while (cond) { __builtin_amdgcn_s_sleep(1); \
;     if ((++_sp & 255u) == 0u) { if (xb_ld(&(bar)[XB_TMO])) break; if (_sp > XB_SPIN_CAP) { atomicAdd(&(bar)[XB_TMO], 1u); break; } } } } while (0)
; __device__ __forceinline__ void xcd_barrier(const XcdBarrier& b) {
;     asm volatile("s_waitcnt vmcnt(0)" ::: "memory");
;     __syncthreads();
;     if (threadIdx.x == 0) {
;         unsigned* bar = b.bar;
;         __builtin_amdgcn_s_waitcnt(0);
;         unsigned nloc = b.st[0], nx = b.st[1];
;         if (nloc == 0u) { xcd_barrier_complete(bar, b.x, nloc, nx); b.st[0] = nloc; b.st[1] = nx; }
;         const unsigned old = xb_add(&bar[XB_XSUB(b.x)], 1u);
;         const unsigned gen = old / nloc;
;         if (old + 1u == (gen + 1u) * nloc) {
;             __builtin_amdgcn_fence(__ATOMIC_RELEASE, "agent");
;             asm volatile("s_waitcnt vmcnt(0)" ::: "memory");
;             const unsigned og = xb_add(&bar[XB_TOP], 1u);
;             const unsigned tg = og / nx;
;             if (og + 1u == (tg + 1u) * nx) xb_add(&bar[XB_TOPGEN], 1u);
;             else XB_SPIN(xb_ld(&bar[XB_TOPGEN]) == tg, bar);
;             __builtin_amdgcn_fence(__ATOMIC_ACQUIRE, "agent");
;             xb_add(&bar[XB_XGEN(b.x)], 1u);
;             asm volatile("s_waitcnt vmcnt(0)" ::: "memory");
;         } else {
;             XB_SPIN(xb_ld(&bar[XB_XGEN(b.x)]) == gen, bar);
;             __builtin_amdgcn_fence(__ATOMIC_ACQUIRE, "agent");
;             asm volatile("s_waitcnt vmcnt(0)" ::: "memory");
;         }
;     }
;     __syncthreads();
.LBB0_715:
	s_cmp_gt_i32 s71, 5
	s_cselect_b64 s[0:1], -1, 0
	s_and_b64 s[4:5], s[6:7], s[0:1]
	s_andn2_b64 vcc, exec, s[4:5]
	s_cbranch_vccnz .LBB0_769
	s_waitcnt vmcnt(0)
	s_waitcnt vmcnt(0) lgkmcnt(0)
	s_barrier
	s_and_saveexec_b64 s[4:5], s[96:97]
	s_cbranch_execz .LBB0_768
	s_cmp_eq_u32 s99, 1
	s_cbranch_scc0 .Lgb4_global
	s_and_b32 s100, s2, 7
	s_lshl_b32 s100, s100, 8
	s_add_u32 s100, s100, 0x2d800
	v_mov_b32_e32 v254, s100
	v_mov_b32_e32 v255, 1
	global_atomic_add v254, v255, s[76:77]
	s_mov_b32 s100, 0
.Lgb4_loop:
	global_load_dword v253, v254, s[76:77] sc1
	s_waitcnt vmcnt(0)
	v_readfirstlane_b32 s98, v253
	s_cmp_ge_u32 s98, 96
	s_cbranch_scc1 .Lgb4_acq
	s_sleep 1
	s_add_u32 s100, s100, 1
	s_cmp_lt_u32 s100, 0x40000
	s_cbranch_scc1 .Lgb4_loop

; __device__ __forceinline__ unsigned xb_ld(unsigned* p)              { return __hip_atomic_load(p, __ATOMIC_RELAXED, __HIP_MEMORY_SCOPE_AGENT); }
; __device__ __forceinline__ unsigned xb_add(unsigned* p, unsigned v) { return __hip_atomic_fetch_add(p, v, __ATOMIC_RELAXED, __HIP_MEMORY_SCOPE_AGENT); }
; #define XB_SPIN(cond, bar) do { unsigned _sp = 0; while (cond) { __builtin_amdgcn_s_sleep(1); \
;     if ((++_sp & 255u) == 0u) { if (xb_ld(&(bar)[XB_TMO])) break; if (_sp > XB_SPIN_CAP) { atomicAdd(&(bar)[XB_TMO], 1u); break; } } } } while (0)
; __device__ __forceinline__ void xcd_barrier(const XcdBarrier& b) {
;     asm volatile("s_waitcnt vmcnt(0)" ::: "memory");
;     __syncthreads();
;     if (threadIdx.x == 0) {
;         unsigned* bar = b.bar;
;         __builtin_amdgcn_s_waitcnt(0);
;         unsigned nloc = b.st[0], nx = b.st[1];
;         if (nloc == 0u) { xcd_barrier_complete(bar, b.x, nloc, nx); b.st[0] = nloc; b.st[1] = nx; }
;         const unsigned old = xb_add(&bar[XB_XSUB(b.x)], 1u);
;         const unsigned gen = old / nloc;
;         if (old + 1u == (gen + 1u) * nloc) {
;             __builtin_amdgcn_fence(__ATOMIC_RELEASE, "agent");
;             asm volatile("s_waitcnt vmcnt(0)" ::: "memory");
;             const unsigned og = xb_add(&bar[XB_TOP], 1u);
;             const unsigned tg = og / nx;
;             if (og + 1u == (tg + 1u) * nx) xb_add(&bar[XB_TOPGEN], 1u);
;             else XB_SPIN(xb_ld(&bar[XB_TOPGEN]) == tg, bar);
;             __builtin_amdgcn_fence(__ATOMIC_ACQUIRE, "agent");
;             xb_add(&bar[XB_XGEN(b.x)], 1u);
;             asm volatile("s_waitcnt vmcnt(0)" ::: "memory");
;         } else {
;             XB_SPIN(xb_ld(&bar[XB_XGEN(b.x)]) == gen, bar);
;             __builtin_amdgcn_fence(__ATOMIC_ACQUIRE, "agent");
;             asm volatile("s_waitcnt vmcnt(0)" ::: "memory");
;         }
;     }
;     __syncthreads();
.LBB0_786:
	s_cmp_gt_i32 s71, 6
	s_cselect_b64 s[0:1], -1, 0
	s_and_b64 s[4:5], s[4:5], s[0:1]
	s_andn2_b64 vcc, exec, s[4:5]
	s_cbranch_vccnz .LBB0_840
	s_waitcnt vmcnt(0)
	s_waitcnt vmcnt(0) lgkmcnt(0)
	s_barrier
	s_and_saveexec_b64 s[4:5], s[96:97]
	s_cbranch_execz .LBB0_839
	s_cmp_eq_u32 s99, 1
	s_cbranch_scc0 .Lgb5_global
	s_and_b32 s100, s2, 7
	s_lshl_b32 s100, s100, 8
	s_add_u32 s100, s100, 0x2d800
	v_mov_b32_e32 v254, s100
	v_mov_b32_e32 v255, 1
	global_atomic_add v254, v255, s[76:77]
	s_mov_b32 s100, 0
.Lgb5_loop:
	global_load_dword v253, v254, s[76:77] sc1
	s_waitcnt vmcnt(0)
	v_readfirstlane_b32 s98, v253
	s_cmp_ge_u32 s98, 128
	s_cbranch_scc1 .Lgb5_acq
	s_sleep 1
	s_add_u32 s100, s100, 1
	s_cmp_lt_u32 s100, 0x40000
	s_cbranch_scc1 .Lgb5_loop
